# conv item entry: first row loads issued before waiting for the per-item weight loads (one exposed load latency instead of two)
# baseline (speedup 1.0000x reference)
; __device__ __forceinline__ void item_conv(const Params& p, int l, int item) {
;   const float* cw = p.conv_w + l * 3 * 512;
;   for (int e = threadIdx.x; e < 128 * 64; e += NTHR) {
;     int tok = item * 128 + (e >> 6), c = (e & 63) * 8;
;     int t, b; bool samp = tok >= NP;
;     if (!samp) { t = tok & 2047; b = tok >> 11; } else { int ts = tok - NP; t = ts & 15; b = ts >> 4; }
;     float y[8];
; #pragma unroll
;     for (int i = 0; i < 8; ++i) y[i] = 0.f;
; #pragma unroll
;     for (int j = 0; j < 3; ++j) {
;       int pi = t + j;
;       float f[8];
;       if (pi >= 2) {
;         uint4 raw = *reinterpret_cast<const uint4*>(p.u + (long)(tok - 2 + j) * 512 + c);
;         unsigned w[4] = {raw.x, raw.y, raw.z, raw.w};
; #pragma unroll
;         for (int i = 0; i < 4; ++i) { f[2 * i] = __uint_as_float(w[i] << 16); f[2 * i + 1] = __uint_as_float(w[i] & 0xffff0000u); }
;       } else if (samp) {
;         const float* ps = p.cconv + ((long)(l * 16 + b) * 2 + pi) * 512 + c;
; #pragma unroll
;         for (int i = 0; i < 8; ++i) f[i] = ps[i];
;       } else {
; #pragma unroll
;         for (int i = 0; i < 8; ++i) f[i] = 0.f;
;       }
; #pragma unroll
;       for (int i = 0; i < 8; ++i) y[i] += f[i] * cw[j * 512 + c + i];
.LBB0_487:
	s_waitcnt vmcnt(0)
	v_readlane_b32 s28, v246, 25
	v_readlane_b32 s29, v246, 26
	v_readlane_b32 s26, v246, 16
	v_readlane_b32 s4, v248, 59
	v_readlane_b32 s5, v248, 60
	v_readlane_b32 s6, v248, 63
	v_readlane_b32 s7, v247, 0
	v_readlane_b32 s8, v248, 24
	v_readlane_b32 s9, v248, 25
	v_and_b32_e32 v249, 63, v188
	v_lshlrev_b32_e32 v251, 5, v249
	v_lshlrev_b32_e32 v249, 4, v249
	v_lshlrev_b32_e32 v250, 4, v188
	v_readfirstlane_b32 s10, v210
	s_add_u32 s12, s28, 0x1000
	s_addc_u32 s13, s29, 0
	global_load_dwordx4 v[36:39], v251, s[28:29]
	global_load_dwordx4 v[40:43], v251, s[28:29] offset:16
	global_load_dwordx4 v[44:47], v251, s[28:29] offset:2048
	global_load_dwordx4 v[48:51], v251, s[28:29] offset:2064
	global_load_dwordx4 v[52:55], v251, s[12:13]
	global_load_dwordx4 v[56:59], v251, s[12:13] offset:16
	s_lshl_b32 s11, s46, 7
	s_add_i32 s10, s10, s11
	s_mov_b32 s11, 0
	s_cmp_gt_u32 s10, 0xffff
	s_cselect_b32 s13, 1, 0
	s_and_b32 s12, s10, 0x7ff
	s_cmp_lg_u32 s13, 0
	s_cbranch_scc0 .Lcv_tp0e
	s_and_b32 s12, s10, 15
.Lcv_tp0e:
	s_add_i32 s14, s10, -2
	s_ashr_i32 s15, s14, 31
	s_lshl_b64 s[14:15], s[14:15], 10
	s_add_u32 s0, s4, s14
	s_addc_u32 s1, s5, s15
	s_lshl_b32 s14, s10, 10
	s_add_u32 s2, s6, s14
	s_addc_u32 s3, s7, 0
	s_cmp_lt_u32 s12, 2
	s_cbranch_scc1 .Lcv_e_slow
	global_load_dwordx4 v[0:3], v249, s[0:1]
	global_load_dwordx4 v[4:7], v249, s[0:1] offset:1024
	global_load_dwordx4 v[8:11], v249, s[0:1] offset:2048
	global_load_dwordx4 v[12:15], v249, s[2:3]
	s_waitcnt vmcnt(4)
	ds_write_b128 v250, v[36:39]
	ds_write_b128 v250, v[40:43] offset:8192
	ds_write_b128 v250, v[44:47] offset:16384
	ds_write_b128 v250, v[48:51] offset:24576
	ds_write_b128 v250, v[52:55] offset:32768
	ds_write_b128 v250, v[56:59] offset:40960
	s_waitcnt lgkmcnt(0)
	s_branch .Lcv_first
.Lcv_e_slow:
	s_waitcnt vmcnt(0)
	ds_write_b128 v250, v[36:39]
	ds_write_b128 v250, v[40:43] offset:8192
	ds_write_b128 v250, v[44:47] offset:16384
	ds_write_b128 v250, v[48:51] offset:24576
	ds_write_b128 v250, v[52:55] offset:32768
	ds_write_b128 v250, v[56:59] offset:40960
	s_waitcnt lgkmcnt(0)
	s_branch .Lcv_slow

; __device__ __forceinline__ unsigned pack2(float a, float b) { unsigned r; asm volatile("v_cvt_pk_bf16_f32 %0, %1, %2" : "=v"(r) : "v"(a), "v"(b)); return r; }
; __device__ __forceinline__ void item_conv(const Params& p, int l, int item) {
;     ...
;   for (int e = threadIdx.x; e < 128 * 64; e += NTHR) {
;     int tok = item * 128 + (e >> 6), c = (e & 63) * 8;
;     int t, b; bool samp = tok >= NP;
;     if (!samp) { t = tok & 2047; b = tok >> 11; } else { int ts = tok - NP; t = ts & 15; b = ts >> 4; }
;     float y[8];
; #pragma unroll
;     for (int i = 0; i < 8; ++i) y[i] = 0.f;
; #pragma unroll
;     for (int j = 0; j < 3; ++j) {
;       int pi = t + j;
;       float f[8];
;       if (pi >= 2) {
;         uint4 raw = *reinterpret_cast<const uint4*>(p.u + (long)(tok - 2 + j) * 512 + c);
;         unsigned w[4] = {raw.x, raw.y, raw.z, raw.w};
; #pragma unroll
;         for (int i = 0; i < 4; ++i) { f[2 * i] = __uint_as_float(w[i] << 16); f[2 * i + 1] = __uint_as_float(w[i] & 0xffff0000u); }
;       } else if (samp) {
;         const float* ps = p.cconv + ((long)(l * 16 + b) * 2 + pi) * 512 + c;
; #pragma unroll
;         for (int i = 0; i < 8; ++i) f[i] = ps[i];
;       } else {
; #pragma unroll
;         for (int i = 0; i < 8; ++i) f[i] = 0.f;
;       }
; #pragma unroll
;       for (int i = 0; i < 8; ++i) y[i] += f[i] * cw[j * 512 + c + i];
;     }
;     uint4 graw = *reinterpret_cast<const uint4*>(p.gza + (long)tok * 512 + c);
;     unsigned gw[4] = {graw.x, graw.y, graw.z, graw.w};
;     uint4 o;
;     unsigned ow[4];
; #pragma unroll
;     for (int i = 0; i < 4; ++i) {
;       float g0 = __uint_as_float(gw[i] << 16), g1 = __uint_as_float(gw[i] & 0xffff0000u);
;       ow[i] = pack2(g0 * y[2 * i], g1 * y[2 * i + 1]);
;     }
;     o.x = ow[0]; o.y = ow[1]; o.z = ow[2]; o.w = ow[3];
;     *reinterpret_cast<uint4*>(p.gza + (long)tok * 512 + c) = o;
.Lcv_tp0:
	s_add_i32 s14, s10, -2
	s_ashr_i32 s15, s14, 31
	s_lshl_b64 s[14:15], s[14:15], 10
	s_add_u32 s0, s4, s14
	s_addc_u32 s1, s5, s15
	s_lshl_b32 s14, s10, 10
	s_add_u32 s2, s6, s14
	s_addc_u32 s3, s7, 0
	s_cmp_lt_u32 s12, 2
	s_cbranch_scc1 .Lcv_slow
	global_load_dwordx4 v[0:3], v249, s[0:1]
	global_load_dwordx4 v[4:7], v249, s[0:1] offset:1024
	global_load_dwordx4 v[8:11], v249, s[0:1] offset:2048
	global_load_dwordx4 v[12:15], v249, s[2:3]
.Lcv_first:
	s_waitcnt vmcnt(0)
.Lcv_fast:
	ds_read_b128 v[16:19], v250
	ds_read_b128 v[20:23], v250 offset:8192
	ds_read_b128 v[24:27], v250 offset:16384
	ds_read_b128 v[28:31], v250 offset:24576
	s_waitcnt vmcnt(4)
	v_lshlrev_b32_e32 v32, 16, v0
	v_lshlrev_b32_e32 v33, 16, v1
	v_lshlrev_b32_e32 v34, 16, v2
	v_lshlrev_b32_e32 v190, 16, v3
	v_and_b32_e32 v0, 0xffff0000, v0
	v_and_b32_e32 v1, 0xffff0000, v1
	v_and_b32_e32 v2, 0xffff0000, v2
	v_and_b32_e32 v3, 0xffff0000, v3
	s_waitcnt lgkmcnt(2)
	v_fma_f32 v16, v32, v16, 0
	v_fma_f32 v17, v0, v17, 0
	v_fma_f32 v18, v33, v18, 0
	v_fma_f32 v19, v1, v19, 0
	v_fma_f32 v20, v34, v20, 0
	v_fma_f32 v21, v2, v21, 0
	v_fma_f32 v22, v190, v22, 0
	v_fma_f32 v23, v3, v23, 0
	s_waitcnt vmcnt(3)
	v_lshlrev_b32_e32 v32, 16, v4
	v_lshlrev_b32_e32 v33, 16, v5
	v_lshlrev_b32_e32 v34, 16, v6
	v_lshlrev_b32_e32 v190, 16, v7
	v_and_b32_e32 v4, 0xffff0000, v4
	v_and_b32_e32 v5, 0xffff0000, v5
	v_and_b32_e32 v6, 0xffff0000, v6
	v_and_b32_e32 v7, 0xffff0000, v7
	s_waitcnt lgkmcnt(0)
	v_fmac_f32_e32 v16, v32, v24
	v_fmac_f32_e32 v17, v4, v25
	v_fmac_f32_e32 v18, v33, v26
	v_fmac_f32_e32 v19, v5, v27
	v_fmac_f32_e32 v20, v34, v28
	v_fmac_f32_e32 v21, v6, v29
	v_fmac_f32_e32 v22, v190, v30
	v_fmac_f32_e32 v23, v7, v31
	ds_read_b128 v[24:27], v250 offset:32768
	ds_read_b128 v[28:31], v250 offset:40960
	s_waitcnt vmcnt(2)
	v_lshlrev_b32_e32 v32, 16, v8
	v_lshlrev_b32_e32 v33, 16, v9
	v_lshlrev_b32_e32 v34, 16, v10
	v_lshlrev_b32_e32 v190, 16, v11
	v_and_b32_e32 v8, 0xffff0000, v8
	v_and_b32_e32 v9, 0xffff0000, v9
	v_and_b32_e32 v10, 0xffff0000, v10
	v_and_b32_e32 v11, 0xffff0000, v11
	s_waitcnt lgkmcnt(0)
	v_fmac_f32_e32 v16, v32, v24
	v_fmac_f32_e32 v17, v8, v25
	v_fmac_f32_e32 v18, v33, v26
	v_fmac_f32_e32 v19, v9, v27
	v_fmac_f32_e32 v20, v34, v28
	v_fmac_f32_e32 v21, v10, v29
	v_fmac_f32_e32 v22, v190, v30
	v_fmac_f32_e32 v23, v11, v31
	s_waitcnt vmcnt(1)
	v_lshlrev_b32_e32 v32, 16, v12
	v_lshlrev_b32_e32 v33, 16, v13
	v_lshlrev_b32_e32 v34, 16, v14
	v_lshlrev_b32_e32 v190, 16, v15
	v_and_b32_e32 v12, 0xffff0000, v12
	v_and_b32_e32 v13, 0xffff0000, v13
	v_and_b32_e32 v14, 0xffff0000, v14
	v_and_b32_e32 v15, 0xffff0000, v15
	v_mul_f32_e32 v32, v16, v32
	v_mul_f32_e32 v12, v17, v12
	v_mul_f32_e32 v33, v18, v33
	v_mul_f32_e32 v13, v19, v13
	v_mul_f32_e32 v34, v20, v34
	v_mul_f32_e32 v14, v21, v14
	v_mul_f32_e32 v190, v22, v190
	v_mul_f32_e32 v15, v23, v15
	v_cvt_pk_bf16_f32 v16, v32, v12
	v_cvt_pk_bf16_f32 v17, v33, v13
	v_cvt_pk_bf16_f32 v18, v34, v14
	v_cvt_pk_bf16_f32 v19, v190, v15
	s_mov_b64 s[16:17], s[2:3]
	s_add_i32 s11, s11, 1
	s_cmp_eq_u32 s11, 16
	s_cbranch_scc1 .Lcv_last
	s_add_i32 s10, s10, 8
	s_and_b32 s12, s10, 0x7ff
	s_cmp_lg_u32 s13, 0
	s_cbranch_scc0 .Lcv_tp1
	s_and_b32 s12, s10, 15
